# v79 + SSM carry split over the two S1 workgroups of a group (own half each, half-1 waits for half-0's end state)
# baseline (speedup 1.0000x reference)
.LBB0_256:
	s_add_u32 s20, s78, 0x4e00000
	s_addc_u32 s18, s79, 0
	s_lshl_b32 s0, s62, 8
	s_add_i32 s0, s0, s39
	v_or_b32_e32 v68, s0, v84
	v_lshl_or_b32 v67, s38, 7, v67
	s_and_b32 s21, s18, 0xffff
	s_mov_b32 s23, 0x20000
	s_mov_b32 s22, 0x7ffffff0
	v_lshl_or_b32 v67, v68, 9, v67
	s_waitcnt vmcnt(0)
	s_barrier
	buffer_store_dwordx4 v[62:65], v67, s[20:23], 0 offen sc1
	buffer_store_dwordx4 v[58:61], v67, s[20:23], 0 offen offset:64 sc1
	v_cmp_eq_u32_e32 vcc, 0, v66
	s_nop 0
	v_add_u32_e32 v58, 0x2000, v67
	buffer_store_dwordx4 v[54:57], v58, s[20:23], 0 offen sc1
	buffer_store_dwordx4 v[50:53], v58, s[20:23], 0 offen offset:64 sc1
	s_nop 1
	v_add_u32_e32 v50, 0x4000, v67
	buffer_store_dwordx4 v[46:49], v50, s[20:23], 0 offen sc1
	buffer_store_dwordx4 v[42:45], v50, s[20:23], 0 offen offset:64 sc1
	s_nop 1
	v_add_u32_e32 v42, 0x6000, v67
	buffer_store_dwordx4 v[38:41], v42, s[20:23], 0 offen sc1
	buffer_store_dwordx4 v[34:37], v42, s[20:23], 0 offen offset:64 sc1
	s_nop 1
	v_add_u32_e32 v34, 0x10000, v67
	buffer_store_dwordx4 v[30:33], v34, s[20:23], 0 offen sc1
	buffer_store_dwordx4 v[26:29], v34, s[20:23], 0 offen offset:64 sc1
	s_nop 1
	v_add_u32_e32 v26, 0x12000, v67
	buffer_store_dwordx4 v[22:25], v26, s[20:23], 0 offen sc1
	buffer_store_dwordx4 v[18:21], v26, s[20:23], 0 offen offset:64 sc1
	s_nop 1
	v_add_u32_e32 v18, 0x14000, v67
	buffer_store_dwordx4 v[14:17], v18, s[20:23], 0 offen sc1
	buffer_store_dwordx4 v[10:13], v18, s[20:23], 0 offen offset:64 sc1
	s_nop 1
	v_add_u32_e32 v10, 0x16000, v67
	buffer_store_dwordx4 v[6:9], v10, s[20:23], 0 offen sc1
	buffer_store_dwordx4 v[2:5], v10, s[20:23], 0 offen offset:64 sc1
	s_waitcnt vmcnt(0)
	s_waitcnt vmcnt(0)
	s_barrier
	v_readlane_b32 s96, v254, 37
	v_mov_b32_e32 v3, 0
	s_bfe_u32 s27, s96, 0x10003
	s_lshl_b32 s27, s27, 8
	s_lshl_b32 s38, s24, 8
	s_add_u32 s38, s78, s38
	s_addc_u32 s39, s79, 0
	s_add_u32 s38, s38, 0xe81c000
	s_addc_u32 s39, s39, 0
	s_add_u32 s40, s78, 0xe804000
	s_addc_u32 s41, s79, 0
	v_and_b32_e32 v152, 63, v66
	v_lshl_or_b32 v152, s24, 6, v152
	v_lshlrev_b32_e32 v152, 3, v152
	v_and_b32_e32 v7, 63, v66
	v_lshl_or_b32 v4, s24, 6, v7
	v_ashrrev_i32_e32 v5, 31, v4
	v_lshl_add_u64 v[4:5], v[4:5], 3, s[78:79]
	v_add_co_u32_e32 v4, vcc, 0xe800000, v4
	s_add_i32 s0, 0, 0x20040
	s_nop 0
	v_addc_co_u32_e32 v5, vcc, 0, v5, vcc
	global_load_dwordx2 v[4:5], v[4:5], off
	v_or_b32_e32 v10, 0xc00, v66
	v_lshrrev_b32_e32 v11, 6, v66
	v_lshlrev_b32_e32 v13, 3, v66
	v_or_b32_e32 v6, 0x400, v66
	v_lshl_add_u32 v33, v7, 3, s0
	v_lshlrev_b32_e32 v7, 2, v7
	v_lshlrev_b32_e32 v39, 4, v10
	v_or_b32_e32 v8, 0x800, v66
	v_or_b32_e32 v12, 0x1000, v66
	v_add_u32_e32 v24, s0, v13
	v_cmp_eq_u32_e64 s[0:1], 1, v11
	v_cmp_eq_u32_e64 s[16:17], 2, v11
	v_cmp_eq_u32_e64 s[4:5], 3, v11
	v_cmp_eq_u32_e64 s[6:7], 4, v11
	v_cmp_eq_u32_e64 s[8:9], 5, v11
	v_cmp_eq_u32_e64 s[10:11], 6, v11
	v_cmp_eq_u32_e64 s[12:13], 7, v11
	v_cmp_eq_u32_e64 s[14:15], 8, v11
	v_lshrrev_b32_e32 v35, 3, v6
	v_lshlrev_b32_e32 v37, 4, v6
	v_lshl_or_b32 v6, v11, 14, v7
	v_mov_b32_e32 v9, 2.0
	v_or_b32_e32 v18, 0x1c00, v66
	v_and_b32_e32 v20, 56, v13
	v_lshl_add_u32 v25, v12, 4, 0
	v_lshlrev_b32_e32 v38, 4, v8
	v_lshlrev_b32_e32 v40, 4, v12
	v_lshlrev_b32_e32 v15, 9, v1
	v_or_b32_e32 v14, 0x1400, v66
	v_lshl_add_u32 v31, v18, 4, 0
	v_lshlrev_b32_e32 v43, 4, v18
	v_lshl_add_u32 v18, v20, 2, 0
	v_lshl_add_u32 v27, v14, 4, 0
	v_lshlrev_b32_e32 v41, 4, v14
	v_add_u32_e32 v45, v18, v15
	v_add_u32_e32 v17, 0x200, v66
	v_or_b32_e32 v16, 0x1800, v66
	v_lshl_add_u32 v29, v16, 4, 0
	v_lshrrev_b32_e32 v34, 3, v17
	v_lshlrev_b32_e32 v42, 4, v16
	v_add_u32_e32 v19, 0x600, v66
	v_lshrrev_b32_e32 v36, 3, v19
	v_lshl_add_u32 v23, v66, 4, 0
	v_lshlrev_b32_e32 v19, 9, v34
	v_lshlrev_b32_e32 v21, 9, v35
	v_lshlrev_b32_e32 v22, 9, v36
	s_lshl_b32 s19, s24, 9
	s_mov_b64 s[58:59], 0
	v_lshlrev_b32_e32 v2, 4, v66
	s_mov_b32 s21, 0xffff
	v_add_u32_e32 v26, 0x12000, v23
	v_add_u32_e32 v28, 0x16000, v23
	v_add_u32_e32 v30, 0x1a000, v23
	v_add_u32_e32 v32, 0x1e000, v23
	v_add_u32_e32 v44, 0, v6
	s_mov_b32 s24, 0xffff0000
	s_movk_i32 s25, 0x500
	s_mov_b64 s[22:23], 0x3a00400
	s_mov_b32 s26, 0x3a00000
	v_add_u32_e32 v46, v18, v19
	v_add_u32_e32 v47, v18, v21
	v_add_u32_e32 v48, v18, v22
	v_mov_b32_e32 v18, v3
	v_mov_b32_e32 v19, v3
	s_waitcnt vmcnt(0)
	v_mul_f32_e32 v10, v4, v4
	v_pk_fma_f32 v[10:11], v[4:5], v[4:5], v[10:11] op_sel_hi:[1,1,0] neg_lo:[1,0,0] neg_hi:[1,0,0]
	v_add_f32_e32 v12, v4, v4
	v_mov_b32_e32 v8, v5
	v_mov_b32_e32 v13, v11
	v_pk_mul_f32 v[12:13], v[12:13], v[8:9]
	v_mov_b32_e32 v14, v11
	v_pk_mov_b32 v[10:11], v[10:11], v[12:13] op_sel:[1,0]
	v_mov_b32_e32 v15, v13
	v_pk_mul_f32 v[10:11], v[10:11], v[14:15]
	v_pk_mul_f32 v[16:17], v[12:13], v[12:13] op_sel_hi:[0,1]
	v_pk_fma_f32 v[12:13], v[12:13], v[12:13], v[10:11] op_sel_hi:[0,1,1] neg_lo:[1,0,0] neg_hi:[1,0,0]
	v_pk_mul_f32 v[14:15], v[10:11], v[16:17]
	v_mov_b32_e32 v8, v12
	v_mov_b32_e32 v10, v15
	v_pk_mul_f32 v[14:15], v[12:13], v[8:9] op_sel_hi:[0,1]
	v_pk_fma_f32 v[12:13], v[12:13], v[8:9], v[10:11] op_sel_hi:[0,1,1] neg_lo:[0,0,1] neg_hi:[0,0,1]
	v_pk_mul_f32 v[10:11], v[14:15], v[10:11]
	v_add_f32_e32 v15, v12, v12
	v_mov_b32_e32 v13, v11
	v_mul_f32_e32 v8, v11, v11
	v_pk_fma_f32 v[12:13], v[12:13], v[12:13], v[8:9] op_sel_hi:[1,1,0] neg_lo:[0,0,1] neg_hi:[0,0,1]
	v_pk_mov_b32 v[6:7], v[4:5], v[4:5] op_sel:[1,0]
	v_mov_b32_e32 v10, v12
	v_mov_b32_e32 v14, v12
	v_pk_mul_f32 v[10:11], v[10:11], v[14:15]
	s_nop 0
	v_pk_mov_b32 v[12:13], v[10:11], v[12:13] op_sel:[1,0]
	v_mov_b32_e32 v8, v11
	v_pk_mul_f32 v[14:15], v[12:13], v[8:9]
	v_pk_fma_f32 v[16:17], v[12:13], v[8:9], v[10:11] neg_lo:[1,0,0] neg_hi:[1,0,0]
	v_pk_mul_f32 v[14:15], v[10:11], v[14:15]
	v_mov_b32_e32 v8, v16
	v_mov_b32_e32 v10, v16
	v_mov_b32_e32 v11, v16
	v_mov_b32_e32 v9, v15
	v_mov_b32_e32 v12, v15
	v_mov_b32_e32 v13, v15
	v_pk_mov_b32 v[14:15], v[14:15], v[16:17] op_sel:[1,0]
	v_lshlrev_b32_e32 v16, 1, v20

.LBB0_265:
	v_add_u32_e32 v17, s27, v44
	ds_read2st64_b32 v[50:51], v17 offset1:1
	v_pk_mul_f32 v[52:53], v[6:7], v[22:23] op_sel_hi:[1,0]
	s_addk_i32 s27, 0x1000
	v_pk_fma_f32 v[54:55], v[4:5], v[20:21], v[52:53] neg_lo:[0,0,1] neg_hi:[0,0,1]
	v_pk_fma_f32 v[20:21], v[4:5], v[20:21], v[52:53] op_sel_hi:[1,0,1]
	s_cmpk_eq_i32 s27, 0x4000
	v_mov_b32_e32 v55, v21
	s_waitcnt lgkmcnt(0)
	v_pk_add_f32 v[20:21], v[54:55], v[50:51]
	ds_read2st64_b32 v[50:51], v17 offset0:2 offset1:3
	v_pk_mul_f32 v[52:53], v[6:7], v[20:21] op_sel:[0,1]
	s_nop 0
	v_pk_fma_f32 v[54:55], v[4:5], v[20:21], v[52:53] neg_lo:[0,0,1] neg_hi:[0,0,1]
	v_pk_fma_f32 v[20:21], v[4:5], v[20:21], v[52:53] op_sel_hi:[1,0,1]
	s_nop 0
	v_mov_b32_e32 v55, v21
	s_waitcnt lgkmcnt(0)
	v_pk_add_f32 v[20:21], v[54:55], v[50:51]
	ds_read2st64_b32 v[50:51], v17 offset0:4 offset1:5
	v_pk_mul_f32 v[52:53], v[6:7], v[20:21] op_sel:[0,1]
	s_nop 0
	v_pk_fma_f32 v[54:55], v[4:5], v[20:21], v[52:53] neg_lo:[0,0,1] neg_hi:[0,0,1]
	v_pk_fma_f32 v[20:21], v[4:5], v[20:21], v[52:53] op_sel_hi:[1,0,1]
	s_nop 0
	v_mov_b32_e32 v55, v21
	s_waitcnt lgkmcnt(0)
	v_pk_add_f32 v[20:21], v[54:55], v[50:51]
	ds_read2st64_b32 v[50:51], v17 offset0:6 offset1:7
	v_pk_mul_f32 v[52:53], v[6:7], v[20:21] op_sel:[0,1]
	s_nop 0
	v_pk_fma_f32 v[54:55], v[4:5], v[20:21], v[52:53] neg_lo:[0,0,1] neg_hi:[0,0,1]
	v_pk_fma_f32 v[20:21], v[4:5], v[20:21], v[52:53] op_sel_hi:[1,0,1]
	s_nop 0
	v_mov_b32_e32 v55, v21
	s_waitcnt lgkmcnt(0)
	v_pk_add_f32 v[20:21], v[54:55], v[50:51]
	ds_read2st64_b32 v[50:51], v17 offset0:8 offset1:9
	v_pk_mul_f32 v[52:53], v[6:7], v[20:21] op_sel:[0,1]
	s_nop 0
	v_pk_fma_f32 v[54:55], v[4:5], v[20:21], v[52:53] neg_lo:[0,0,1] neg_hi:[0,0,1]
	v_pk_fma_f32 v[20:21], v[4:5], v[20:21], v[52:53] op_sel_hi:[1,0,1]
	s_nop 0
	v_mov_b32_e32 v55, v21
	s_waitcnt lgkmcnt(0)
	v_pk_add_f32 v[20:21], v[54:55], v[50:51]
	ds_read2st64_b32 v[50:51], v17 offset0:10 offset1:11
	v_pk_mul_f32 v[52:53], v[6:7], v[20:21] op_sel:[0,1]
	s_nop 0
	v_pk_fma_f32 v[54:55], v[4:5], v[20:21], v[52:53] neg_lo:[0,0,1] neg_hi:[0,0,1]
	v_pk_fma_f32 v[20:21], v[4:5], v[20:21], v[52:53] op_sel_hi:[1,0,1]
	s_nop 0
	v_mov_b32_e32 v55, v21
	s_waitcnt lgkmcnt(0)
	v_pk_add_f32 v[20:21], v[54:55], v[50:51]
	ds_read2st64_b32 v[50:51], v17 offset0:12 offset1:13
	v_pk_mul_f32 v[52:53], v[6:7], v[20:21] op_sel:[0,1]
	s_nop 0
	v_pk_fma_f32 v[54:55], v[4:5], v[20:21], v[52:53] neg_lo:[0,0,1] neg_hi:[0,0,1]
	v_pk_fma_f32 v[20:21], v[4:5], v[20:21], v[52:53] op_sel_hi:[1,0,1]
	s_nop 0
	v_mov_b32_e32 v55, v21
	s_waitcnt lgkmcnt(0)
	v_pk_add_f32 v[20:21], v[54:55], v[50:51]
	ds_read2st64_b32 v[50:51], v17 offset0:14 offset1:15
	v_pk_mul_f32 v[52:53], v[6:7], v[20:21] op_sel:[0,1]
	s_nop 0
	v_pk_fma_f32 v[54:55], v[4:5], v[20:21], v[52:53] neg_lo:[0,0,1] neg_hi:[0,0,1]
	v_pk_fma_f32 v[20:21], v[4:5], v[20:21], v[52:53] op_sel_hi:[1,0,1]
	s_nop 0
	v_mov_b32_e32 v55, v21
	s_waitcnt lgkmcnt(0)
	v_pk_add_f32 v[20:21], v[54:55], v[50:51]
	s_nop 0
	v_mov_b32_e32 v22, v21
	s_cbranch_scc0 .LBB0_265
	ds_write_b64 v24, v[20:21]
	s_waitcnt lgkmcnt(0)
	s_bitcmp1_b32 s96, 3
	s_cbranch_scc0 .Lcarry_nowait
	v_cmp_eq_u32_e32 vcc, 0, v66
	s_and_saveexec_b64 s[42:43], vcc
	s_cbranch_execz .Lcarry_polled
	v_mov_b32_e32 v153, 0
	s_movk_i32 s44, 0x1000
.Lcarry_poll:
	global_load_dword v154, v153, s[38:39] sc1
	s_waitcnt vmcnt(0)
	v_cmp_ne_u32_e32 vcc, 0, v154
	s_cbranch_vccnz .Lcarry_polled
	s_sleep 1
	s_add_i32 s44, s44, -1
	s_cmp_lg_u32 s44, 0
	s_cbranch_scc1 .Lcarry_poll
.Lcarry_polled:
	s_or_b64 exec, exec, s[42:43]
.Lcarry_nowait:
	s_barrier
	s_bitcmp1_b32 s96, 3
	s_cbranch_scc0 .Lcarry_nostate
	global_load_dwordx2 v[18:19], v152, s[40:41] sc1
	s_waitcnt vmcnt(0)
.Lcarry_nostate:
	ds_read2st64_b64 v[50:53], v33 offset1:1
	v_pk_mul_f32 v[20:21], v[14:15], v[18:19] op_sel:[0,1]
	s_mov_b32 s27, 0
	v_pk_fma_f32 v[54:55], v[8:9], v[18:19], v[20:21] neg_lo:[0,0,1] neg_hi:[0,0,1]
	v_pk_fma_f32 v[20:21], v[8:9], v[18:19], v[20:21] op_sel_hi:[1,0,1]
	s_nop 0
	v_mov_b32_e32 v55, v21
	s_waitcnt lgkmcnt(0)
	v_pk_add_f32 v[20:21], v[54:55], v[50:51]
	s_nop 0
	v_cndmask_b32_e64 v17, v19, v21, s[0:1]
	v_cndmask_b32_e64 v49, v18, v20, s[0:1]
	v_pk_mul_f32 v[18:19], v[8:9], v[20:21]
	s_nop 0
	v_sub_f32_e32 v18, v18, v19
	v_add_f32_e32 v22, v52, v18
	v_pk_mul_f32 v[18:19], v[14:15], v[20:21]
	v_cndmask_b32_e64 v49, v49, v22, s[16:17]
	v_add_f32_e32 v18, v18, v19
	v_add_f32_e32 v50, v53, v18
	ds_read2st64_b64 v[18:21], v33 offset0:2 offset1:3
	v_cndmask_b32_e64 v17, v17, v50, s[16:17]
	v_pk_mul_f32 v[50:51], v[14:15], v[50:51] op_sel_hi:[1,0]
	s_nop 0
	v_pk_fma_f32 v[52:53], v[8:9], v[22:23], v[50:51] neg_lo:[0,0,1] neg_hi:[0,0,1]
	v_pk_fma_f32 v[50:51], v[8:9], v[22:23], v[50:51] op_sel_hi:[1,0,1]
	s_nop 0
	v_mov_b32_e32 v53, v51
	s_waitcnt lgkmcnt(0)
	v_pk_add_f32 v[18:19], v[18:19], v[52:53]
	s_nop 0
	v_mul_f32_e32 v22, v9, v19
	v_pk_fma_f32 v[50:51], v[8:9], v[18:19], v[22:23] op_sel_hi:[1,1,0] neg_lo:[0,0,1] neg_hi:[0,0,1]
	v_mul_f32_e32 v22, v8, v19
	v_cndmask_b32_e64 v17, v17, v19, s[4:5]
	v_cndmask_b32_e64 v49, v49, v18, s[4:5]
	v_pk_fma_f32 v[18:19], v[8:9], v[18:19], v[22:23] op_sel:[0,1,0] op_sel_hi:[1,0,0]
	s_nop 0
	v_mov_b32_e32 v51, v19
	v_pk_add_f32 v[50:51], v[20:21], v[50:51]
	ds_read2st64_b64 v[18:21], v33 offset0:4 offset1:5
	v_pk_mul_f32 v[52:53], v[12:13], v[50:51]
	v_cndmask_b32_e64 v17, v17, v51, s[6:7]
	v_cndmask_b32_e64 v22, v49, v50, s[6:7]
	v_pk_fma_f32 v[54:55], v[10:11], v[50:51], v[52:53] op_sel:[0,0,1] op_sel_hi:[1,1,0] neg_lo:[0,0,1] neg_hi:[0,0,1]
	v_pk_fma_f32 v[50:51], v[10:11], v[50:51], v[52:53] op_sel:[0,0,1] op_sel_hi:[1,1,0]
	s_nop 0
	v_mov_b32_e32 v55, v51
	s_waitcnt lgkmcnt(0)
	v_pk_add_f32 v[18:19], v[18:19], v[54:55]
	s_nop 0
	v_pk_mul_f32 v[50:51], v[12:13], v[18:19]
	v_cndmask_b32_e64 v17, v17, v19, s[8:9]
	v_cndmask_b32_e64 v22, v22, v18, s[8:9]
	v_pk_fma_f32 v[52:53], v[10:11], v[18:19], v[50:51] op_sel:[0,0,1] op_sel_hi:[1,1,0] neg_lo:[0,0,1] neg_hi:[0,0,1]
	v_pk_fma_f32 v[18:19], v[10:11], v[18:19], v[50:51] op_sel:[0,0,1] op_sel_hi:[1,1,0]
	s_nop 0
	v_mov_b32_e32 v53, v19
	v_pk_add_f32 v[50:51], v[20:21], v[52:53]
	ds_read2st64_b64 v[18:21], v33 offset0:6 offset1:7
	v_pk_mul_f32 v[52:53], v[12:13], v[50:51]
	v_cndmask_b32_e64 v17, v17, v51, s[10:11]
	v_cndmask_b32_e64 v22, v22, v50, s[10:11]
	v_pk_fma_f32 v[54:55], v[10:11], v[50:51], v[52:53] op_sel:[0,0,1] op_sel_hi:[1,1,0] neg_lo:[0,0,1] neg_hi:[0,0,1]
	v_pk_fma_f32 v[50:51], v[10:11], v[50:51], v[52:53] op_sel:[0,0,1] op_sel_hi:[1,1,0]
	s_nop 0
	v_mov_b32_e32 v55, v51
	s_waitcnt lgkmcnt(0)
	v_pk_add_f32 v[18:19], v[18:19], v[54:55]
	s_nop 0
	v_cndmask_b32_e64 v49, v22, v18, s[12:13]
	v_mul_f32_e32 v22, v9, v19
	v_pk_fma_f32 v[50:51], v[8:9], v[18:19], v[22:23] op_sel_hi:[1,1,0] neg_lo:[0,0,1] neg_hi:[0,0,1]
	v_mul_f32_e32 v22, v8, v19
	v_cndmask_b32_e64 v17, v17, v19, s[12:13]
	v_pk_fma_f32 v[18:19], v[8:9], v[18:19], v[22:23] op_sel:[0,1,0] op_sel_hi:[1,0,0]
	s_nop 0
	v_mov_b32_e32 v51, v19
	v_pk_add_f32 v[18:19], v[20:21], v[50:51]
	s_nop 0
	v_cndmask_b32_e64 v20, v17, v19, s[14:15]
	v_cndmask_b32_e64 v17, v49, v18, s[14:15]
	s_bitcmp1_b32 s96, 3
	s_cbranch_scc1 .Lcarry_nopub
	v_cmp_gt_u32_e32 vcc, 64, v66
	s_and_saveexec_b64 s[42:43], vcc
	s_cbranch_execz .Lcarry_pubdone
	global_store_dwordx2 v152, v[18:19], s[40:41] sc1
	s_waitcnt vmcnt(0)
	v_cmp_eq_u32_e32 vcc, 0, v66
	s_and_b64 exec, exec, vcc
	s_cbranch_execz .Lcarry_pubdone
	v_mov_b32_e32 v153, 0
	v_mov_b32_e32 v154, 1
	global_atomic_add v153, v154, s[38:39]

.Lcarry_nopub:
.LBB0_267:
	v_add_u32_e32 v22, s27, v44
	ds_read2st64_b32 v[50:51], v22 offset1:1
	v_cvt_pk_bf16_f32 v49, v17, v20
	v_mul_f32_e32 v21, v5, v20
	v_mul_f32_e32 v20, v4, v20
	v_fma_f32 v21, v4, v17, -v21
	v_fmac_f32_e32 v20, v5, v17
	s_waitcnt lgkmcnt(0)
	v_add_f32_e32 v50, v50, v21
	v_add_f32_e32 v17, v20, v51
	ds_read2st64_b32 v[20:21], v22 offset0:2 offset1:3
	v_cvt_pk_bf16_f32 v51, v50, v17
	ds_write2st64_b32 v22, v49, v51 offset1:2
	v_mul_f32_e32 v49, v5, v17
	v_mul_f32_e32 v17, v4, v17
	v_fma_f32 v49, v4, v50, -v49
	v_fmac_f32_e32 v17, v5, v50
	s_waitcnt lgkmcnt(1)
	v_add_f32_e32 v49, v20, v49
	v_add_f32_e32 v17, v17, v21
	ds_read2st64_b32 v[20:21], v22 offset0:4 offset1:5
	v_cvt_pk_bf16_f32 v50, v49, v17
	v_mul_f32_e32 v51, v5, v17
	v_mul_f32_e32 v17, v4, v17
	v_fma_f32 v51, v4, v49, -v51
	v_fmac_f32_e32 v17, v5, v49
	s_waitcnt lgkmcnt(0)
	v_add_f32_e32 v51, v20, v51
	v_add_f32_e32 v17, v17, v21
	ds_read2st64_b32 v[20:21], v22 offset0:6 offset1:7
	v_cvt_pk_bf16_f32 v49, v51, v17
	ds_write2st64_b32 v22, v50, v49 offset0:4 offset1:6
	v_mul_f32_e32 v49, v5, v17
	v_mul_f32_e32 v17, v4, v17
	v_fma_f32 v49, v4, v51, -v49
	v_fmac_f32_e32 v17, v5, v51
	s_waitcnt lgkmcnt(1)
	v_add_f32_e32 v49, v20, v49
	v_add_f32_e32 v17, v17, v21
	ds_read2st64_b32 v[20:21], v22 offset0:8 offset1:9
	v_cvt_pk_bf16_f32 v50, v49, v17
	v_mul_f32_e32 v51, v5, v17
	v_mul_f32_e32 v17, v4, v17
	v_fma_f32 v51, v4, v49, -v51
	v_fmac_f32_e32 v17, v5, v49
	s_waitcnt lgkmcnt(0)
	v_add_f32_e32 v51, v20, v51
	v_add_f32_e32 v17, v17, v21
	ds_read2st64_b32 v[20:21], v22 offset0:10 offset1:11
	v_cvt_pk_bf16_f32 v49, v51, v17
	ds_write2st64_b32 v22, v50, v49 offset0:8 offset1:10
	v_mul_f32_e32 v49, v5, v17
	v_mul_f32_e32 v17, v4, v17
	v_fma_f32 v49, v4, v51, -v49
	v_fmac_f32_e32 v17, v5, v51
	s_waitcnt lgkmcnt(1)
	v_add_f32_e32 v49, v20, v49
	v_add_f32_e32 v17, v17, v21
	ds_read2st64_b32 v[20:21], v22 offset0:12 offset1:13
	v_cvt_pk_bf16_f32 v50, v49, v17
	v_mul_f32_e32 v51, v5, v17
	v_mul_f32_e32 v17, v4, v17
	v_fma_f32 v51, v4, v49, -v51
	v_fmac_f32_e32 v17, v5, v49
	s_waitcnt lgkmcnt(0)
	v_add_f32_e32 v51, v20, v51
	v_add_f32_e32 v49, v17, v21
	ds_read2st64_b32 v[20:21], v22 offset0:14 offset1:15
	v_cvt_pk_bf16_f32 v17, v51, v49
	ds_write2st64_b32 v22, v50, v17 offset0:12 offset1:14
	v_mul_f32_e32 v17, v5, v49
	v_fma_f32 v17, v4, v51, -v17
	s_waitcnt lgkmcnt(1)
	v_add_f32_e32 v17, v20, v17
	v_mul_f32_e32 v20, v4, v49
	v_fmac_f32_e32 v20, v5, v51
	s_addk_i32 s27, 0x1000
	v_add_f32_e32 v20, v20, v21
	s_cmpk_eq_i32 s27, 0x4000
	s_cbranch_scc0 .LBB0_267
	s_waitcnt lgkmcnt(0)
	s_barrier
	ds_read_b128 v[50:53], v45
	ds_read_b128 v[54:57], v45 offset:16
	v_mov_b64_e32 v[20:21], s[78:79]
	s_movk_i32 s27, 0x100
	s_waitcnt lgkmcnt(1)
	v_lshlrev_b32_e32 v17, 16, v51
	v_and_or_b32 v58, v50, s21, v17
	v_lshlrev_b32_e32 v17, 16, v53
	v_and_or_b32 v59, v52, s21, v17
	s_waitcnt lgkmcnt(0)
	v_lshlrev_b32_e32 v17, 16, v55
	v_and_or_b32 v60, v54, s21, v17
	v_lshlrev_b32_e32 v17, 16, v57
	v_and_or_b32 v61, v56, s21, v17
	v_lshrrev_b32_e32 v17, 16, v50
	v_and_or_b32 v50, v51, s24, v17
	v_lshrrev_b32_e32 v17, 16, v52
	v_and_or_b32 v51, v53, s24, v17
	v_lshrrev_b32_e32 v17, 16, v54
	v_and_or_b32 v52, v55, s24, v17
	v_lshrrev_b32_e32 v17, 16, v56
	v_and_or_b32 v53, v57, s24, v17
	v_or_b32_e32 v17, s58, v1
	v_mad_i64_i32 v[54:55], s[30:31], v17, s25, v[20:21]
	v_mov_b32_e32 v17, v3
	v_lshl_add_u64 v[54:55], v[54:55], 0, v[16:17]
	v_lshl_add_u64 v[56:57], v[54:55], 0, s[22:23]
	v_add_co_u32_e32 v54, vcc, s26, v54
	s_nop 1
	v_addc_co_u32_e32 v55, vcc, 0, v55, vcc
	global_store_dwordx4 v[54:55], v[58:61], off offset:1024
	global_store_dwordx4 v[56:57], v[50:53], off offset:128
	ds_read_b128 v[50:53], v46
	ds_read_b128 v[54:57], v46 offset:16
	s_waitcnt lgkmcnt(1)
	v_lshlrev_b32_e32 v22, 16, v51
	v_and_or_b32 v58, v50, s21, v22
	v_lshlrev_b32_e32 v22, 16, v53
	v_and_or_b32 v59, v52, s21, v22
	s_waitcnt lgkmcnt(0)
	v_lshlrev_b32_e32 v22, 16, v55
	v_and_or_b32 v60, v54, s21, v22
	v_lshlrev_b32_e32 v22, 16, v57
	v_and_or_b32 v61, v56, s21, v22
	v_lshrrev_b32_e32 v22, 16, v50
	v_and_or_b32 v50, v51, s24, v22
	v_lshrrev_b32_e32 v22, 16, v52
	v_and_or_b32 v51, v53, s24, v22
	v_lshrrev_b32_e32 v22, 16, v54
	v_and_or_b32 v52, v55, s24, v22
	v_lshrrev_b32_e32 v22, 16, v56
	v_and_or_b32 v53, v57, s24, v22
	v_or_b32_e32 v22, s58, v34
	v_mad_i64_i32 v[54:55], s[30:31], v22, s25, v[20:21]
	v_lshl_add_u64 v[54:55], v[54:55], 0, v[16:17]
	v_lshl_add_u64 v[56:57], v[54:55], 0, s[22:23]
	v_add_co_u32_e32 v54, vcc, s26, v54
	s_nop 1
	v_addc_co_u32_e32 v55, vcc, 0, v55, vcc
	global_store_dwordx4 v[54:55], v[58:61], off offset:1024
	global_store_dwordx4 v[56:57], v[50:53], off offset:128
	ds_read_b128 v[50:53], v47
	ds_read_b128 v[54:57], v47 offset:16
	s_waitcnt lgkmcnt(1)
	v_lshlrev_b32_e32 v22, 16, v51
	v_and_or_b32 v58, v50, s21, v22
	v_lshlrev_b32_e32 v22, 16, v53
	v_and_or_b32 v59, v52, s21, v22
	s_waitcnt lgkmcnt(0)
	v_lshlrev_b32_e32 v22, 16, v55
	v_and_or_b32 v60, v54, s21, v22
	v_lshlrev_b32_e32 v22, 16, v57
	v_and_or_b32 v61, v56, s21, v22
	v_lshrrev_b32_e32 v22, 16, v50
	v_and_or_b32 v50, v51, s24, v22
	v_lshrrev_b32_e32 v22, 16, v52
	v_and_or_b32 v51, v53, s24, v22
	v_lshrrev_b32_e32 v22, 16, v54
	v_and_or_b32 v52, v55, s24, v22
	v_lshrrev_b32_e32 v22, 16, v56
	v_and_or_b32 v53, v57, s24, v22
	v_or_b32_e32 v22, s58, v35
	v_mad_i64_i32 v[54:55], s[30:31], v22, s25, v[20:21]
	v_lshl_add_u64 v[54:55], v[54:55], 0, v[16:17]
	v_lshl_add_u64 v[56:57], v[54:55], 0, s[22:23]
	v_add_co_u32_e32 v54, vcc, s26, v54
	s_nop 1
	v_addc_co_u32_e32 v55, vcc, 0, v55, vcc
	global_store_dwordx4 v[54:55], v[58:61], off offset:1024
	global_store_dwordx4 v[56:57], v[50:53], off offset:128
	ds_read_b128 v[50:53], v48
	ds_read_b128 v[54:57], v48 offset:16
	s_waitcnt lgkmcnt(1)
	v_lshlrev_b32_e32 v22, 16, v51
	v_and_or_b32 v58, v50, s21, v22
	v_lshlrev_b32_e32 v22, 16, v53
	v_and_or_b32 v59, v52, s21, v22
	s_waitcnt lgkmcnt(0)
	v_lshlrev_b32_e32 v22, 16, v55
	v_and_or_b32 v60, v54, s21, v22
	v_lshlrev_b32_e32 v22, 16, v57
	v_and_or_b32 v61, v56, s21, v22
	v_lshrrev_b32_e32 v22, 16, v50
	v_and_or_b32 v50, v51, s24, v22
	v_lshrrev_b32_e32 v22, 16, v52
	v_and_or_b32 v51, v53, s24, v22
	v_lshrrev_b32_e32 v22, 16, v54
	v_and_or_b32 v52, v55, s24, v22
	v_lshrrev_b32_e32 v22, 16, v56
	v_and_or_b32 v53, v57, s24, v22
	v_add_u32_e32 v22, s58, v36
	v_mad_i64_i32 v[20:21], s[30:31], v22, s25, v[20:21]
	v_lshl_add_u64 v[20:21], v[20:21], 0, v[16:17]
	v_lshl_add_u64 v[54:55], v[20:21], 0, s[22:23]
	v_add_co_u32_e32 v20, vcc, 0x3a00000, v20
	s_mov_b64 s[58:59], 0
	s_nop 0
	v_addc_co_u32_e32 v21, vcc, 0, v21, vcc
	s_and_b64 vcc, exec, s[56:57]
	global_store_dwordx4 v[20:21], v[58:61], off offset:1024
	global_store_dwordx4 v[54:55], v[50:53], off offset:128
	s_barrier
	s_cbranch_vccz .LBB0_264
